# first barrier (after weight prep) uses the XCD-hierarchical barrier instead of the cooperative grid sync
# baseline (speedup 1.0000x reference)
.LBB0_215:
	v_readlane_b32 s4, v235, 46
	v_readlane_b32 s5, v235, 47
	v_readlane_b32 s46, v236, 13
	s_and_b64 vcc, exec, s[4:5]
	v_readlane_b32 s47, v236, 14
	s_waitcnt vmcnt(0)
	s_waitcnt lgkmcnt(0)
	s_barrier
	s_mov_b64 s[2:3], exec
	v_readlane_b32 s4, v238, 43
	v_readlane_b32 s5, v238, 44
	s_and_b64 s[4:5], s[2:3], s[4:5]
	s_mov_b64 exec, s[4:5]
	s_cbranch_execz .LBB0_269
	v_readlane_b32 s4, v235, 40
	s_waitcnt vmcnt(0) expcnt(0) lgkmcnt(0)
	s_nop 0
	v_mov_b32_e32 v0, s4
	ds_read_b32 v2, v0
	v_readlane_b32 s4, v235, 41
	s_waitcnt lgkmcnt(0)
	v_cmp_ne_u32_e32 vcc, 0, v2
	v_mov_b32_e32 v0, s4
	ds_read_b32 v0, v0
	s_cbranch_vccnz .LBB0_232
	s_mov_b32 s10, 1
	s_branch .LBB0_220
